# attention main loops: row-sum adds spread over the PV MFMA gaps (96-dim: 16 in-place pair sums + tree; 64-dim: same, s1 exps kept in v219..v234)
# speedup vs baseline: 1.0562x; 1.0081x over previous
.LBB0_338:
	v_exp_f32_e32 v64, v64
	v_exp_f32_e32 v219, v48
	v_exp_f32_e32 v65, v65
	v_exp_f32_e32 v220, v49
	v_exp_f32_e32 v66, v66
	v_exp_f32_e32 v221, v50
	v_exp_f32_e32 v67, v67
	v_exp_f32_e32 v222, v51
	s_cmp_eq_u32 s98, 0
	s_cbranch_scc1 .Lstg_x_3
	s_waitcnt lgkmcnt(0)
	s_barrier
.Lstg_x_3:
	v_exp_f32_e32 v68, v68
	v_exp_f32_e32 v223, v52
	v_exp_f32_e32 v69, v69
	v_exp_f32_e32 v224, v53
	v_exp_f32_e32 v70, v70
	v_exp_f32_e32 v225, v54
	v_exp_f32_e32 v71, v71
	v_exp_f32_e32 v226, v55
	v_exp_f32_e32 v72, v72
	v_exp_f32_e32 v227, v56
	v_exp_f32_e32 v73, v73
	v_exp_f32_e32 v228, v57
	v_exp_f32_e32 v74, v74
	v_exp_f32_e32 v229, v58
	v_exp_f32_e32 v75, v75
	v_exp_f32_e32 v230, v59
	v_exp_f32_e32 v76, v76
	v_exp_f32_e32 v231, v60
	v_exp_f32_e32 v77, v77
	v_exp_f32_e32 v232, v61
	v_exp_f32_e32 v78, v78
	v_exp_f32_e32 v233, v62
	v_exp_f32_e32 v79, v79
	v_exp_f32_e32 v234, v63
	v_cvt_pk_bf16_f32 v48, v64, v65
	v_cvt_pk_bf16_f32 v49, v66, v67
	v_cvt_pk_bf16_f32 v50, v68, v69
	v_cvt_pk_bf16_f32 v51, v70, v71
	v_cvt_pk_bf16_f32 v52, v72, v73
	v_cvt_pk_bf16_f32 v53, v74, v75
	v_cvt_pk_bf16_f32 v54, v76, v77
	v_cvt_pk_bf16_f32 v55, v78, v79
	v_cvt_pk_bf16_f32 v56, v219, v220
	v_cvt_pk_bf16_f32 v57, v221, v222
	v_cvt_pk_bf16_f32 v58, v223, v224
	v_cvt_pk_bf16_f32 v59, v225, v226
	v_cvt_pk_bf16_f32 v60, v227, v228
	v_cvt_pk_bf16_f32 v61, v229, v230
	v_cvt_pk_bf16_f32 v62, v231, v232
	v_cvt_pk_bf16_f32 v63, v233, v234
	s_setprio 1
	s_cmp_lg_u32 s98, 0
	s_cbranch_scc1 .Lstg_y_4
	s_waitcnt lgkmcnt(0)
	s_barrier
.Lstg_y_4:
	s_mul_i32 s9, s77, 0x2400
	v_add_u32_e32 v235, s9, v199
	ds_read_b128 v[160:163], v235
	ds_read_b128 v[156:159], v235 offset:32
	ds_read_b128 v[164:167], v235 offset:4608
	ds_read_b128 v[152:155], v235 offset:4640
	ds_read_b128 v[144:147], v235 offset:64
	ds_read_b128 v[140:143], v235 offset:96
	ds_read_b128 v[148:151], v235 offset:4672
	ds_read_b128 v[136:139], v235 offset:4704
	s_waitcnt lgkmcnt(14)
	v_mfma_f32_32x32x16_bf16 v[16:31], v[128:131], v[48:51], v[16:31]
	v_add_f32_e32 v64, v64, v219
	v_add_f32_e32 v65, v65, v220
	v_add_f32_e32 v66, v66, v221
	v_add_f32_e32 v67, v67, v222
	v_add_f32_e32 v68, v68, v223
	s_mul_i32 s9, s8, 0x2400
	s_cmp_eq_u32 s33, 1
	s_cselect_b32 s18, 0, 0x2400
	s_add_i32 s76, s76, 1
	v_lshl_add_u64 v[190:191], v[190:191], 0, s[20:21]
	v_lshl_add_u64 v[192:193], v[192:193], 0, s[22:23]
	s_cmp_eq_u32 s76, 31
	s_waitcnt lgkmcnt(13)
	v_mfma_f32_32x32x16_bf16 v[0:15], v[132:135], v[48:51], v[0:15]
	v_add_f32_e32 v69, v69, v224
	v_add_f32_e32 v70, v70, v225
	v_add_f32_e32 v71, v71, v226
	v_add_f32_e32 v72, v72, v227
	v_add_f32_e32 v73, v73, v228
	v_add_u32_e32 v48, s9, v177
	s_waitcnt vmcnt(1)
	ds_write_b128 v48, v[104:107]
	v_add_u32_e32 v48, s18, v198
	v_add_u32_e32 v48, 0x4800, v48
	s_waitcnt vmcnt(0)
	ds_write2_b64 v48, v[96:97], v[98:99] offset1:2
	v_mfma_f32_32x32x16_bf16 v[16:31], v[116:119], v[52:55], v[16:31]
	v_add_f32_e32 v74, v74, v229
	v_add_f32_e32 v75, v75, v230
	v_add_f32_e32 v76, v76, v231
	v_add_f32_e32 v77, v77, v232
	v_add_f32_e32 v78, v78, v233
	s_waitcnt lgkmcnt(14)
	v_mfma_f32_32x32x16_bf16 v[0:15], v[120:123], v[52:55], v[0:15]
	v_add_f32_e32 v79, v79, v234
	v_add_f32_e32 v64, v64, v65
	v_add_f32_e32 v66, v66, v67
	v_add_f32_e32 v68, v68, v69
	v_add_f32_e32 v70, v70, v71
	s_waitcnt lgkmcnt(13)
	v_mfma_f32_32x32x16_bf16 v[16:31], v[112:115], v[56:59], v[16:31]
	v_add_f32_e32 v72, v72, v73
	v_add_f32_e32 v74, v74, v75
	v_add_f32_e32 v76, v76, v77
	v_add_f32_e32 v78, v78, v79
	s_waitcnt lgkmcnt(11)
	v_mfma_f32_32x32x16_bf16 v[0:15], v[124:127], v[56:59], v[0:15]
	v_add_f32_e32 v64, v64, v66
	v_add_f32_e32 v68, v68, v70
	v_add_f32_e32 v72, v72, v74
	v_add_f32_e32 v76, v76, v78
	v_mfma_f32_32x32x16_bf16 v[16:31], v[108:111], v[60:63], v[16:31]
	v_add_f32_e32 v64, v64, v68
	v_add_f32_e32 v72, v72, v76
	v_add_f32_e32 v64, v64, v72
	v_add_f32_e32 v194, v194, v64
	s_waitcnt lgkmcnt(10)
	v_mfma_f32_32x32x16_bf16 v[0:15], v[100:103], v[60:63], v[0:15]
	s_cbranch_scc1 .LBB0_340
	s_mov_b32 s33, s77
	s_mov_b32 s77, s8
	s_branch .LBB0_336

.Lstg_y_12:
	s_mul_i32 s8, s45, 0x3400
	v_add_u32_e32 v189, s8, v208
	ds_read_b128 v[60:63], v189
	ds_read_b128 v[156:159], v189 offset:32
	ds_read_b128 v[164:167], v189 offset:6656
	ds_read_b128 v[152:155], v189 offset:64
	ds_read_b128 v[160:163], v189 offset:6688
	ds_read_b128 v[148:151], v189 offset:6720
	s_waitcnt lgkmcnt(13)
	v_mfma_f32_32x32x16_bf16 v[16:31], v[140:143], v[224:227], v[16:31]
	v_add_f32_e32 v64, v64, v219
	v_add_f32_e32 v48, v48, v220
	v_add_f32_e32 v49, v49, v221
	v_add_f32_e32 v50, v50, v222
	s_mul_i32 s44, s43, 0x3400
	s_add_i32 s18, s44, 0
	s_waitcnt lgkmcnt(11)
	v_mfma_f32_32x32x16_bf16 v[0:15], v[144:147], v[224:227], v[0:15]
	v_add_f32_e32 v51, v51, v68
	v_add_f32_e32 v52, v52, v69
	v_add_f32_e32 v53, v53, v70
	v_add_f32_e32 v54, v54, v71
	v_mfma_f32_32x32x16_bf16 v[16:31], v[128:131], v[228:231], v[16:31]
	v_add_f32_e32 v55, v55, v72
	v_add_f32_e32 v56, v56, v73
	v_add_f32_e32 v57, v57, v74
	v_add_f32_e32 v58, v58, v75
	s_waitcnt lgkmcnt(10)
	v_mfma_f32_32x32x16_bf16 v[0:15], v[132:135], v[228:231], v[0:15]
	v_add_f32_e32 v59, v59, v76
	v_add_f32_e32 v65, v65, v77
	v_add_f32_e32 v66, v66, v78
	v_add_f32_e32 v67, v67, v79
	s_waitcnt lgkmcnt(9)
	v_mfma_f32_32x32x16_bf16 v[16:31], v[124:127], v[232:235], v[16:31]
	v_add_f32_e32 v64, v64, v48
	v_add_f32_e32 v49, v49, v50
	v_add_f32_e32 v51, v51, v52
	v_add_f32_e32 v53, v53, v54
	s_waitcnt lgkmcnt(7)
	v_mfma_f32_32x32x16_bf16 v[0:15], v[136:139], v[232:235], v[0:15]
	v_add_f32_e32 v55, v55, v56
	v_add_f32_e32 v57, v57, v58
	v_add_f32_e32 v59, v59, v65
	v_add_f32_e32 v66, v66, v67
	v_mfma_f32_32x32x16_bf16 v[16:31], v[120:123], v[236:239], v[16:31]
	v_add_f32_e32 v64, v64, v49
	v_add_f32_e32 v51, v51, v53
	v_add_f32_e32 v55, v55, v57
	v_add_f32_e32 v59, v59, v66
	v_add_u32_e32 v120, s18, v207
	s_waitcnt vmcnt(1)
	ds_write_b128 v120, v[112:115]
	s_waitcnt lgkmcnt(7)
	v_mfma_f32_32x32x16_bf16 v[0:15], v[116:119], v[236:239], v[0:15]
	v_add_f32_e32 v64, v64, v51
	v_add_f32_e32 v55, v55, v59
	s_and_saveexec_b64 s[8:9], s[4:5]
	v_add_u32_e32 v112, s18, v206
	ds_write_b128 v112, v[104:107]
	s_or_b64 exec, exec, s[8:9]
	v_add_f32_e32 v64, v64, v55
	s_cmp_eq_u32 s72, 1
	s_cselect_b32 s8, 0, 0x2400
	v_add_f32_e32 v190, v190, v64
	v_add_u32_e32 v48, s8, v198
	v_add_u32_e32 v48, 0x9800, v48
	s_waitcnt vmcnt(0)
	ds_write2_b64 v48, v[108:109], v[110:111] offset0:128 offset1:130
	s_add_i32 s33, s33, 1
	v_lshl_add_u64 v[194:195], v[194:195], 0, s[36:37]
	s_cmp_eq_u32 s33, 31
	v_lshl_add_u64 v[196:197], v[196:197], 0, s[22:23]
	s_cbranch_scc1 .LBB0_369
	s_mov_b32 s8, s42
	s_mov_b32 s42, s45
	s_branch .LBB0_361
